# fused final-norm epilogue: barrier-free exchange of self-validating row partial sums, XCD-local plain-store path when all 4 partner WGs share the XCC id (sc1 fallback)
# speedup vs baseline: 1.0039x; 1.0039x over previous
_Z4mega6Paramsii:
	s_mov_b32 s16, s2
	s_load_dwordx16 s[36:51], s[0:1], 0x0
	s_load_dwordx8 s[20:27], s[0:1], 0x80
	s_load_dword s2, s[0:1], 0xb0
	s_load_dwordx2 s[90:91], s[0:1], 0xa8
	s_add_u32 s4, s0, 0xa8
	v_and_b32_e32 v194, 0x3ff, v0
	s_addc_u32 s5, s1, 0
	v_cmp_eq_u32_e64 s[14:15], 0, v194
	s_waitcnt lgkmcnt(0)
	v_writelane_b32 v242, s2, 0
	s_getreg_b32 s2, hwreg(HW_REG_XCC_ID, 0, 4)
	s_and_b32 s2, s2, 15
	s_lshl_b32 s3, s16, 2
	s_add_u32 s6, s26, 0x3c10000
	s_addc_u32 s7, s27, 0
	v_mov_b32_e32 v1, s3
	v_mov_b32_e32 v2, s2
	s_and_saveexec_b64 s[2:3], s[14:15]
	global_store_dword v1, v2, s[6:7] sc1
	s_or_b64 exec, exec, s[2:3]
	s_and_saveexec_b64 s[2:3], s[14:15]
	s_cbranch_execz .LBB0_2
	s_add_i32 s6, 0, 0x20000
	v_mov_b32_e32 v1, 0
	v_mov_b32_e32 v2, s6
	s_add_i32 s6, 0, 0x20004
	ds_write_b32 v2, v1
	v_mov_b32_e32 v2, s6
	ds_write_b32 v2, v1

.LBB0_331:
	s_or_b64 exec, exec, s[0:1]
	s_waitcnt lgkmcnt(0)
	s_barrier
	v_mov_b32_e32 v4, 0
	v_mov_b32_e32 v5, 0
	v_mov_b32_e32 v6, 0
	v_mov_b32_e32 v7, 0
	v_lshlrev_b32_e32 v8, 4, v194
	s_lshl_b32 s4, s16, 13
	s_add_u32 s2, s26, 0x3800000
	s_addc_u32 s3, s27, 0
	s_add_u32 s2, s2, s4
	s_addc_u32 s3, s3, 0
	global_store_dwordx4 v8, v[4:7], s[2:3] sc1
	v_mov_b32_e32 v9, v194
	s_cmp_gt_i32 s16, 63
	s_nop 0
	v_readfirstlane_b32 s17, v9
	s_cbranch_scc1 .LBB0_347
	v_lshlrev_b32_e32 v0, 4, v9
	v_add_u32_e32 v1, 0x2000, v0
	v_ashrrev_i32_e32 v2, 31, v1
	v_lshrrev_b32_e32 v2, 22, v2
	v_add_u32_e32 v2, v1, v2
	v_ashrrev_i32_e32 v8, 10, v2
	v_mul_i32_i24_e32 v2, 0x400, v8
	v_sub_u32_e32 v1, v1, v2
	v_lshrrev_b32_e32 v2, 4, v1
	v_bitop3_b32 v1, v2, v1, 32 bitop3:0x6c
	v_ashrrev_i32_e32 v2, 31, v1
	v_lshrrev_b32_e32 v2, 26, v2
	v_add_u32_e32 v2, v1, v2
	v_lshlrev_b32_e32 v4, 3, v8
	s_ashr_i32 s51, s16, 31
	v_ashrrev_i32_e32 v10, 6, v2
	v_and_b32_e32 v4, -16, v4
	s_lshr_b32 s1, s51, 29
	v_add_u32_e32 v4, v10, v4
	s_add_i32 s1, s16, s1
	v_lshrrev_b32_e32 v5, 2, v4
	v_lshlrev_b32_e32 v6, 1, v4
	v_and_b32_e32 v2, 0xc0, v2
	s_and_b32 s2, s1, -8
	s_ashr_i32 s0, s17, 6
	v_and_b32_e32 v3, 3, v10
	v_and_b32_e32 v5, 4, v5
	v_and_b32_e32 v6, 0x1fffd8, v6
	v_sub_u32_e32 v1, v1, v2
	v_mov_b32_e32 v2, 1
	s_sub_i32 s2, s16, s2
	s_ashr_i32 s3, s17, 8
	s_lshl_b32 s50, s0, 10
	v_or3_b32 v3, v3, v5, v6
	v_lshlrev_b32_e32 v5, 5, v8
	v_ashrrev_i16_sdwa v1, v2, sext(v1) dst_sel:DWORD dst_unused:UNUSED_PAD src0_sel:DWORD src1_sel:BYTE_0
	s_lshl_b32 s5, s2, 3
	s_ashr_i32 s1, s1, 3
	v_and_b32_e32 v5, 32, v5
	v_bfe_i32 v11, v1, 0, 16
	s_mul_i32 s4, s2, 9
	s_cmp_lt_i32 s2, 0
	v_add_lshl_u32 v1, v5, v11, 1
	s_cselect_b32 s2, s4, s5
	v_lshl_add_u32 v128, v3, 11, v1
	v_lshl_add_u32 v130, v4, 11, v1
	v_bfe_i32 v1, v9, 27, 1
	s_add_i32 s1, s2, s1
	v_lshrrev_b32_e32 v1, 22, v1
	s_ashr_i32 s2, s1, 31
	v_add_u32_e32 v1, v0, v1
	s_lshr_b32 s2, s2, 28
	v_and_b32_e32 v1, 0xfffffc00, v1
	s_add_i32 s2, s1, s2
	v_sub_u32_e32 v0, v0, v1
	s_ashr_i32 s4, s2, 4
	s_and_b32 s2, s2, -16
	v_lshrrev_b32_e32 v1, 4, v0
	v_ashrrev_i32_e32 v4, 31, v9
	s_sub_i32 s1, s1, s2
	v_bitop3_b32 v0, v1, v0, 32 bitop3:0x6c
	v_lshrrev_b32_e32 v4, 26, v4
	s_bfe_i32 s2, s1, 0x80000
	v_ashrrev_i32_e32 v1, 31, v0
	v_add_u32_e32 v4, v9, v4
	s_bfe_u32 s2, s2, 0x2000d
	v_lshrrev_b32_e32 v1, 26, v1
	v_ashrrev_i32_e32 v13, 6, v4
	s_add_i32 s5, s1, s2
	v_add_u32_e32 v1, v0, v1
	v_lshlrev_b32_e32 v4, 3, v13
	s_bfe_i32 s2, s5, 0x80000
	s_and_b32 s5, s5, 0xfc
	v_ashrrev_i32_e32 v12, 6, v1
	v_and_b32_e32 v4, -16, v4
	s_sub_i32 s1, s1, s5
	v_add_u32_e32 v4, v12, v4
	s_lshl_b32 s4, s4, 2
	s_sext_i32_i16 s2, s2
	s_sext_i32_i8 s1, s1
	v_lshrrev_b32_e32 v5, 2, v4
	v_lshlrev_b32_e32 v6, 1, v4
	v_and_b32_e32 v1, 0xc0, v1
	s_lshr_b32 s2, s2, 2
	s_add_i32 s42, s4, s1
	v_and_b32_e32 v3, 3, v12
	v_and_b32_e32 v5, 4, v5
	v_and_b32_e32 v6, 0x1fffd8, v6
	v_sub_u32_e32 v0, v0, v1
	s_ashr_i32 s43, s42, 31
	s_bfe_i64 s[6:7], s[2:3], 0x100000
	v_or3_b32 v3, v3, v5, v6
	v_lshlrev_b32_e32 v5, 5, v13
	v_ashrrev_i16_sdwa v0, v2, sext(v0) dst_sel:DWORD dst_unused:UNUSED_PAD src0_sel:DWORD src1_sel:BYTE_0
	s_lshl_b64 s[4:5], s[42:43], 19
	s_lshl_b64 s[6:7], s[6:7], 19
	v_and_b32_e32 v5, 32, v5
	v_bfe_i32 v14, v0, 0, 16
	s_add_u32 s46, s80, s6
	v_add_lshl_u32 v0, v5, v14, 1
	s_addc_u32 s47, s81, s7
	s_add_i32 s43, s50, 0
	v_lshl_add_u32 v132, v3, 11, v0
	s_add_i32 m0, s43, 0x10000
	v_lshl_add_u32 v134, v4, 11, v0
	global_load_lds_dwordx4 v132, s[46:47]
	s_add_i32 m0, s43, 0x12000
	s_add_u32 s44, s82, s4
	global_load_lds_dwordx4 v128, s[46:47]
	s_addc_u32 s45, s83, s5
	s_mov_b32 m0, s43
	s_add_i32 s52, s43, 0x2000
	global_load_lds_dwordx4 v134, s[44:45]
	s_mov_b32 m0, s52
	s_add_u32 s4, s46, 0x10000
	global_load_lds_dwordx4 v130, s[44:45]
	s_addc_u32 s5, s47, 0
	s_add_i32 m0, s43, 0x14000
	v_mov_b32_e32 v133, 0
	global_load_lds_dwordx4 v132, s[4:5]
	s_add_i32 m0, s43, 0x16000
	v_mov_b32_e32 v129, v133
	global_load_lds_dwordx4 v128, s[4:5]
	s_add_u32 s4, s44, 0x40000
	s_addc_u32 s5, s45, 0
	s_add_i32 s53, s43, 0x4000
	s_mov_b32 m0, s53
	s_add_i32 s54, s43, 0x6000
	global_load_lds_dwordx4 v134, s[4:5]
	s_mov_b32 m0, s54
	v_mov_b32_e32 v135, v133
	global_load_lds_dwordx4 v130, s[4:5]
	v_mov_b32_e32 v131, v133
	s_mov_b32 s55, 0
	v_lshl_add_u64 v[6:7], s[46:47], 0, v[132:133]
	v_lshl_add_u64 v[4:5], s[46:47], 0, v[128:129]
	v_lshl_add_u64 v[2:3], s[44:45], 0, v[134:135]
	s_cmp_lg_u32 s3, 1
	v_lshl_add_u64 v[0:1], s[44:45], 0, v[130:131]
	s_cbranch_scc1 .LBB0_334
	s_barrier

.LBB0_1169:
	ds_read_b128 v[128:131], v167
	ds_read_b128 v[132:135], v167 offset:1024
	ds_read_b128 v[136:139], v167 offset:2048
	ds_read_b128 v[156:159], v167 offset:3072
	s_add_u32 s6, s40, 0x100
	s_addc_u32 s7, s41, 0
	s_cmp_eq_u32 s65, 40
	s_cselect_b32 s45, s1, s7
	s_cselect_b32 s44, s0, s6
	s_cselect_b32 s43, s39, s64
	s_cselect_b32 s42, s38, s63
	v_lshl_add_u64 v[202:203], s[40:41], 0, v[148:149]
	s_add_i32 m0, s47, 0xc000
	ds_read_b128 v[160:163], v168
	ds_read_b128 v[172:175], v168 offset:1024
	ds_read_b128 v[176:179], v168 offset:2048
	ds_read_b128 v[180:183], v168 offset:3072
	ds_read_b128 v[184:187], v168 offset:4096
	ds_read_b128 v[188:191], v168 offset:5120
	ds_read_b128 v[194:197], v168 offset:6144
	ds_read_b128 v[198:201], v168 offset:7168
	global_load_lds_dwordx4 v[202:203], off
	v_lshl_add_u64 v[202:203], s[40:41], 0, v[150:151]
	s_add_i32 m0, s47, 0xe000
	s_nop 0
	global_load_lds_dwordx4 v[202:203], off
	s_waitcnt lgkmcnt(8)
	s_barrier
	s_waitcnt lgkmcnt(0)
	s_setprio 1
	s_waitcnt lgkmcnt(0)
	v_mfma_f32_16x16x32_bf16 v[124:127], v[128:131], v[160:163], v[124:127]
	v_mfma_f32_16x16x32_bf16 v[120:123], v[136:139], v[160:163], v[120:123]
	v_mfma_f32_16x16x32_bf16 v[108:111], v[128:131], v[176:179], v[108:111]
	v_mfma_f32_16x16x32_bf16 v[104:107], v[136:139], v[176:179], v[104:107]
	v_mfma_f32_16x16x32_bf16 v[92:95], v[128:131], v[184:187], v[92:95]
	v_mfma_f32_16x16x32_bf16 v[88:91], v[136:139], v[184:187], v[88:91]
	v_mfma_f32_16x16x32_bf16 v[76:79], v[128:131], v[194:197], v[76:79]
	v_mfma_f32_16x16x32_bf16 v[72:75], v[136:139], v[194:197], v[72:75]
	v_mfma_f32_16x16x32_bf16 v[124:127], v[132:135], v[172:175], v[124:127]
	v_mfma_f32_16x16x32_bf16 v[120:123], v[156:159], v[172:175], v[120:123]
	v_mfma_f32_16x16x32_bf16 v[108:111], v[132:135], v[180:183], v[108:111]
	v_mfma_f32_16x16x32_bf16 v[104:107], v[156:159], v[180:183], v[104:107]
	v_mfma_f32_16x16x32_bf16 v[92:95], v[132:135], v[188:191], v[92:95]
	v_mfma_f32_16x16x32_bf16 v[88:91], v[156:159], v[188:191], v[88:91]
	v_mfma_f32_16x16x32_bf16 v[76:79], v[132:135], v[198:201], v[76:79]
	v_mfma_f32_16x16x32_bf16 v[72:75], v[156:159], v[198:201], v[72:75]
	s_setprio 0
	s_barrier
	s_add_i32 s28, s57, s46
	v_lshl_add_u64 v[218:219], s[42:43], 0, v[142:143]
	s_mov_b32 m0, s28
	ds_read_b128 v[202:205], v169
	ds_read_b128 v[206:209], v169 offset:1024
	ds_read_b128 v[210:213], v169 offset:2048
	ds_read_b128 v[214:217], v169 offset:3072
	global_load_lds_dwordx4 v[218:219], off
	v_lshl_add_u64 v[220:221], s[42:43], 0, v[146:147]
	s_add_i32 m0, s28, 0x2000
	s_nop 0
	global_load_lds_dwordx4 v[220:221], off
	s_barrier
	s_waitcnt lgkmcnt(0)
	s_setprio 1
	s_waitcnt lgkmcnt(0)
	v_mfma_f32_16x16x32_bf16 v[116:119], v[202:205], v[160:163], v[116:119]
	v_mfma_f32_16x16x32_bf16 v[112:115], v[210:213], v[160:163], v[112:115]
	v_mfma_f32_16x16x32_bf16 v[100:103], v[202:205], v[176:179], v[100:103]
	v_mfma_f32_16x16x32_bf16 v[96:99], v[210:213], v[176:179], v[96:99]
	v_mfma_f32_16x16x32_bf16 v[84:87], v[202:205], v[184:187], v[84:87]
	v_mfma_f32_16x16x32_bf16 v[80:83], v[210:213], v[184:187], v[80:83]
	v_mfma_f32_16x16x32_bf16 v[68:71], v[202:205], v[194:197], v[68:71]
	v_mfma_f32_16x16x32_bf16 v[64:67], v[210:213], v[194:197], v[64:67]
	v_mfma_f32_16x16x32_bf16 v[116:119], v[206:209], v[172:175], v[116:119]
	v_mfma_f32_16x16x32_bf16 v[112:115], v[214:217], v[172:175], v[112:115]
	v_mfma_f32_16x16x32_bf16 v[100:103], v[206:209], v[180:183], v[100:103]
	v_mfma_f32_16x16x32_bf16 v[96:99], v[214:217], v[180:183], v[96:99]
	v_mfma_f32_16x16x32_bf16 v[84:87], v[206:209], v[188:191], v[84:87]
	v_mfma_f32_16x16x32_bf16 v[80:83], v[214:217], v[188:191], v[80:83]
	v_mfma_f32_16x16x32_bf16 v[68:71], v[206:209], v[198:201], v[68:71]
	v_mfma_f32_16x16x32_bf16 v[64:67], v[214:217], v[198:201], v[64:67]
	s_setprio 0
	s_mov_b32 m0, s47
	v_lshl_add_u64 v[222:223], s[44:45], 0, v[140:141]
	s_barrier
	ds_read_b128 v[160:163], v168 offset:16384
	ds_read_b128 v[172:175], v168 offset:17408
	ds_read_b128 v[176:179], v168 offset:18432
	ds_read_b128 v[180:183], v168 offset:19456
	ds_read_b128 v[184:187], v168 offset:20480
	ds_read_b128 v[188:191], v168 offset:21504
	ds_read_b128 v[194:197], v168 offset:22528
	ds_read_b128 v[198:201], v168 offset:23552
	global_load_lds_dwordx4 v[222:223], off
	v_lshl_add_u64 v[224:225], s[44:45], 0, v[144:145]
	s_mov_b32 m0, s48
	s_nop 0
	global_load_lds_dwordx4 v[224:225], off
	s_barrier
	s_waitcnt lgkmcnt(0)
	s_setprio 1
	s_waitcnt lgkmcnt(0)
	v_mfma_f32_16x16x32_bf16 v[60:63], v[128:131], v[160:163], v[60:63]
	v_mfma_f32_16x16x32_bf16 v[56:59], v[136:139], v[160:163], v[56:59]
	v_mfma_f32_16x16x32_bf16 v[44:47], v[128:131], v[176:179], v[44:47]
	v_mfma_f32_16x16x32_bf16 v[40:43], v[136:139], v[176:179], v[40:43]
	v_mfma_f32_16x16x32_bf16 v[28:31], v[128:131], v[184:187], v[28:31]
	v_mfma_f32_16x16x32_bf16 v[24:27], v[136:139], v[184:187], v[24:27]
	v_mfma_f32_16x16x32_bf16 v[12:15], v[128:131], v[194:197], v[12:15]
	v_mfma_f32_16x16x32_bf16 v[8:11], v[136:139], v[194:197], v[8:11]
	v_mfma_f32_16x16x32_bf16 v[60:63], v[132:135], v[172:175], v[60:63]
	v_mfma_f32_16x16x32_bf16 v[56:59], v[156:159], v[172:175], v[56:59]
	v_mfma_f32_16x16x32_bf16 v[44:47], v[132:135], v[180:183], v[44:47]
	v_mfma_f32_16x16x32_bf16 v[40:43], v[156:159], v[180:183], v[40:43]
	v_mfma_f32_16x16x32_bf16 v[28:31], v[132:135], v[188:191], v[28:31]
	v_mfma_f32_16x16x32_bf16 v[24:27], v[156:159], v[188:191], v[24:27]
	v_mfma_f32_16x16x32_bf16 v[12:15], v[132:135], v[198:201], v[12:15]
	v_mfma_f32_16x16x32_bf16 v[8:11], v[156:159], v[198:201], v[8:11]
	s_setprio 0
	s_barrier
	s_add_u32 s40, s42, 0x2c000
	s_addc_u32 s41, s43, 0
	s_add_i32 s28, s58, s46
	v_lshl_add_u64 v[128:129], s[40:41], 0, v[142:143]
	s_mov_b32 m0, s28
	s_nop 0
	global_load_lds_dwordx4 v[128:129], off
	v_lshl_add_u64 v[128:129], s[40:41], 0, v[146:147]
	s_add_i32 m0, s28, 0x2000
	s_nop 0
	global_load_lds_dwordx4 v[128:129], off
	s_waitcnt vmcnt(6)
	s_barrier
	s_setprio 1
	v_mfma_f32_16x16x32_bf16 v[52:55], v[202:205], v[160:163], v[52:55]
	v_mfma_f32_16x16x32_bf16 v[48:51], v[210:213], v[160:163], v[48:51]
	v_mfma_f32_16x16x32_bf16 v[36:39], v[202:205], v[176:179], v[36:39]
	v_mfma_f32_16x16x32_bf16 v[32:35], v[210:213], v[176:179], v[32:35]
	v_mfma_f32_16x16x32_bf16 v[20:23], v[202:205], v[184:187], v[20:23]
	v_mfma_f32_16x16x32_bf16 v[16:19], v[210:213], v[184:187], v[16:19]
	v_mfma_f32_16x16x32_bf16 v[4:7], v[202:205], v[194:197], v[4:7]
	v_mfma_f32_16x16x32_bf16 v[0:3], v[210:213], v[194:197], v[0:3]
	v_mfma_f32_16x16x32_bf16 v[52:55], v[206:209], v[172:175], v[52:55]
	v_mfma_f32_16x16x32_bf16 v[48:51], v[214:217], v[172:175], v[48:51]
	v_mfma_f32_16x16x32_bf16 v[36:39], v[206:209], v[180:183], v[36:39]
	v_mfma_f32_16x16x32_bf16 v[32:35], v[214:217], v[180:183], v[32:35]
	v_mfma_f32_16x16x32_bf16 v[20:23], v[206:209], v[188:191], v[20:23]
	v_mfma_f32_16x16x32_bf16 v[16:19], v[214:217], v[188:191], v[16:19]
	v_mfma_f32_16x16x32_bf16 v[4:7], v[206:209], v[198:201], v[4:7]
	v_mfma_f32_16x16x32_bf16 v[0:3], v[214:217], v[198:201], v[0:3]
	s_setprio 0
	s_add_i32 s28, 0, 0x18000
	v_add_u32_e32 v156, s28, v165
	s_barrier
	ds_read_b128 v[128:131], v156
	ds_read_b128 v[132:135], v156 offset:1024
	ds_read_b128 v[136:139], v156 offset:2048
	ds_read_b128 v[156:159], v156 offset:3072
	s_add_u32 s40, s44, 0xb0000
	s_addc_u32 s41, s45, 0
	s_mov_b32 m0, s49
	v_lshl_add_u64 v[202:203], s[40:41], 0, v[140:141]
	ds_read_b128 v[160:163], v168 offset:32768
	ds_read_b128 v[172:175], v168 offset:33792
	ds_read_b128 v[176:179], v168 offset:34816
	ds_read_b128 v[180:183], v168 offset:35840
	ds_read_b128 v[184:187], v168 offset:36864
	ds_read_b128 v[188:191], v168 offset:37888
	ds_read_b128 v[194:197], v168 offset:38912
	ds_read_b128 v[198:201], v168 offset:39936
	global_load_lds_dwordx4 v[202:203], off
	v_lshl_add_u64 v[202:203], s[40:41], 0, v[144:145]
	s_mov_b32 m0, s50
	s_nop 0
	global_load_lds_dwordx4 v[202:203], off
	s_waitcnt lgkmcnt(8)
	s_barrier
	s_waitcnt lgkmcnt(0)
	s_setprio 1
	s_waitcnt lgkmcnt(0)
	v_mfma_f32_16x16x32_bf16 v[124:127], v[128:131], v[160:163], v[124:127]
	v_mfma_f32_16x16x32_bf16 v[120:123], v[136:139], v[160:163], v[120:123]
	v_mfma_f32_16x16x32_bf16 v[108:111], v[128:131], v[176:179], v[108:111]
	v_mfma_f32_16x16x32_bf16 v[104:107], v[136:139], v[176:179], v[104:107]
	v_mfma_f32_16x16x32_bf16 v[92:95], v[128:131], v[184:187], v[92:95]
	v_mfma_f32_16x16x32_bf16 v[88:91], v[136:139], v[184:187], v[88:91]
	v_mfma_f32_16x16x32_bf16 v[76:79], v[128:131], v[194:197], v[76:79]
	v_mfma_f32_16x16x32_bf16 v[72:75], v[136:139], v[194:197], v[72:75]
	v_mfma_f32_16x16x32_bf16 v[124:127], v[132:135], v[172:175], v[124:127]
	v_mfma_f32_16x16x32_bf16 v[120:123], v[156:159], v[172:175], v[120:123]
	v_mfma_f32_16x16x32_bf16 v[108:111], v[132:135], v[180:183], v[108:111]
	v_mfma_f32_16x16x32_bf16 v[104:107], v[156:159], v[180:183], v[104:107]
	v_mfma_f32_16x16x32_bf16 v[92:95], v[132:135], v[188:191], v[92:95]
	v_mfma_f32_16x16x32_bf16 v[88:91], v[156:159], v[188:191], v[88:91]
	v_mfma_f32_16x16x32_bf16 v[76:79], v[132:135], v[198:201], v[76:79]
	v_mfma_f32_16x16x32_bf16 v[72:75], v[156:159], v[198:201], v[72:75]
	s_setprio 0
	s_barrier
	s_add_i32 s29, 0, 0x1c000
	s_add_i32 s28, s28, s46
	v_add_u32_e32 v171, s29, v165
	v_lshl_add_u64 v[218:219], v[218:219], 0, s[36:37]
	s_mov_b32 m0, s28
	ds_read_b128 v[202:205], v171
	ds_read_b128 v[206:209], v171 offset:1024
	ds_read_b128 v[210:213], v171 offset:2048
	ds_read_b128 v[214:217], v171 offset:3072
	global_load_lds_dwordx4 v[218:219], off
	v_lshl_add_u64 v[218:219], v[220:221], 0, s[36:37]
	s_add_i32 m0, s28, 0x2000
	s_nop 0
	global_load_lds_dwordx4 v[218:219], off
	s_barrier
	s_waitcnt lgkmcnt(0)
	s_setprio 1
	s_waitcnt lgkmcnt(0)
	v_mfma_f32_16x16x32_bf16 v[116:119], v[202:205], v[160:163], v[116:119]
	v_mfma_f32_16x16x32_bf16 v[112:115], v[210:213], v[160:163], v[112:115]
	v_mfma_f32_16x16x32_bf16 v[100:103], v[202:205], v[176:179], v[100:103]
	v_mfma_f32_16x16x32_bf16 v[96:99], v[210:213], v[176:179], v[96:99]
	v_mfma_f32_16x16x32_bf16 v[84:87], v[202:205], v[184:187], v[84:87]
	v_mfma_f32_16x16x32_bf16 v[80:83], v[210:213], v[184:187], v[80:83]
	v_mfma_f32_16x16x32_bf16 v[68:71], v[202:205], v[194:197], v[68:71]
	v_mfma_f32_16x16x32_bf16 v[64:67], v[210:213], v[194:197], v[64:67]
	v_mfma_f32_16x16x32_bf16 v[116:119], v[206:209], v[172:175], v[116:119]
	v_mfma_f32_16x16x32_bf16 v[112:115], v[214:217], v[172:175], v[112:115]
	v_mfma_f32_16x16x32_bf16 v[100:103], v[206:209], v[180:183], v[100:103]
	v_mfma_f32_16x16x32_bf16 v[96:99], v[214:217], v[180:183], v[96:99]
	v_mfma_f32_16x16x32_bf16 v[84:87], v[206:209], v[188:191], v[84:87]
	v_mfma_f32_16x16x32_bf16 v[80:83], v[214:217], v[188:191], v[80:83]
	v_mfma_f32_16x16x32_bf16 v[68:71], v[206:209], v[198:201], v[68:71]
	v_mfma_f32_16x16x32_bf16 v[64:67], v[214:217], v[198:201], v[64:67]
	s_setprio 0
	s_mov_b32 m0, s54
	v_lshl_add_u64 v[218:219], v[222:223], 0, s[36:37]
	s_barrier
	ds_read_b128 v[160:163], v168 offset:49152
	ds_read_b128 v[172:175], v168 offset:50176
	ds_read_b128 v[176:179], v168 offset:51200
	ds_read_b128 v[180:183], v168 offset:52224
	ds_read_b128 v[184:187], v168 offset:53248
	ds_read_b128 v[188:191], v168 offset:54272
	ds_read_b128 v[194:197], v168 offset:55296
	ds_read_b128 v[198:201], v168 offset:56320
	global_load_lds_dwordx4 v[218:219], off
	v_lshl_add_u64 v[218:219], v[224:225], 0, s[36:37]
	s_mov_b32 m0, s55
	s_nop 0
	global_load_lds_dwordx4 v[218:219], off
	s_barrier
	s_waitcnt lgkmcnt(0)
	s_setprio 1
	s_waitcnt lgkmcnt(0)
	v_mfma_f32_16x16x32_bf16 v[60:63], v[128:131], v[160:163], v[60:63]
	v_mfma_f32_16x16x32_bf16 v[56:59], v[136:139], v[160:163], v[56:59]
	v_mfma_f32_16x16x32_bf16 v[44:47], v[128:131], v[176:179], v[44:47]
	v_mfma_f32_16x16x32_bf16 v[40:43], v[136:139], v[176:179], v[40:43]
	v_mfma_f32_16x16x32_bf16 v[28:31], v[128:131], v[184:187], v[28:31]
	v_mfma_f32_16x16x32_bf16 v[24:27], v[136:139], v[184:187], v[24:27]
	v_mfma_f32_16x16x32_bf16 v[12:15], v[128:131], v[194:197], v[12:15]
	v_mfma_f32_16x16x32_bf16 v[8:11], v[136:139], v[194:197], v[8:11]
	v_mfma_f32_16x16x32_bf16 v[60:63], v[132:135], v[172:175], v[60:63]
	v_mfma_f32_16x16x32_bf16 v[56:59], v[156:159], v[172:175], v[56:59]
	v_mfma_f32_16x16x32_bf16 v[44:47], v[132:135], v[180:183], v[44:47]
	v_mfma_f32_16x16x32_bf16 v[40:43], v[156:159], v[180:183], v[40:43]
	v_mfma_f32_16x16x32_bf16 v[28:31], v[132:135], v[188:191], v[28:31]
	v_mfma_f32_16x16x32_bf16 v[24:27], v[156:159], v[188:191], v[24:27]
	v_mfma_f32_16x16x32_bf16 v[12:15], v[132:135], v[198:201], v[12:15]
	v_mfma_f32_16x16x32_bf16 v[8:11], v[156:159], v[198:201], v[8:11]
	s_setprio 0
	s_barrier
	s_add_u32 s40, s42, 0x2c080
	s_addc_u32 s41, s43, 0
	s_add_i32 s28, s29, s46
	v_lshl_add_u64 v[128:129], s[40:41], 0, v[142:143]
	s_mov_b32 m0, s28
	s_nop 0
	global_load_lds_dwordx4 v[128:129], off
	v_lshl_add_u64 v[128:129], s[40:41], 0, v[146:147]
	s_add_i32 m0, s28, 0x2000
	s_nop 0
	global_load_lds_dwordx4 v[128:129], off
	s_waitcnt vmcnt(6)
	s_barrier
	s_setprio 1
	v_mfma_f32_16x16x32_bf16 v[52:55], v[202:205], v[160:163], v[52:55]
	v_mfma_f32_16x16x32_bf16 v[48:51], v[210:213], v[160:163], v[48:51]
	v_mfma_f32_16x16x32_bf16 v[36:39], v[202:205], v[176:179], v[36:39]
	v_mfma_f32_16x16x32_bf16 v[32:35], v[210:213], v[176:179], v[32:35]
	v_mfma_f32_16x16x32_bf16 v[20:23], v[202:205], v[184:187], v[20:23]
	v_mfma_f32_16x16x32_bf16 v[16:19], v[210:213], v[184:187], v[16:19]
	v_mfma_f32_16x16x32_bf16 v[4:7], v[202:205], v[194:197], v[4:7]
	v_mfma_f32_16x16x32_bf16 v[0:3], v[210:213], v[194:197], v[0:3]
	v_mfma_f32_16x16x32_bf16 v[52:55], v[206:209], v[172:175], v[52:55]
	v_mfma_f32_16x16x32_bf16 v[48:51], v[214:217], v[172:175], v[48:51]
	v_mfma_f32_16x16x32_bf16 v[36:39], v[206:209], v[180:183], v[36:39]
	v_mfma_f32_16x16x32_bf16 v[32:35], v[214:217], v[180:183], v[32:35]
	v_mfma_f32_16x16x32_bf16 v[20:23], v[206:209], v[188:191], v[20:23]
	v_mfma_f32_16x16x32_bf16 v[16:19], v[214:217], v[188:191], v[16:19]
	v_mfma_f32_16x16x32_bf16 v[4:7], v[206:209], v[198:201], v[4:7]
	v_mfma_f32_16x16x32_bf16 v[0:3], v[214:217], v[198:201], v[0:3]
	s_setprio 0
	s_add_i32 s65, s65, 2
	s_add_u32 s63, s63, 0x100
	s_addc_u32 s64, s64, 0
	s_cmp_gt_u32 s65, 41
	s_mov_b64 s[40:41], s[6:7]
	s_barrier
	s_cbranch_scc0 .LBB0_1169
	v_lshl_add_u32 v171, s62, 8, v164
	v_lshl_or_b32 v188, s10, 8, v166
	s_mov_b32 s63, 0xffff0000
	v_lshlrev_b32_e32 v128, 11, v171
	v_lshl_add_u32 v128, v188, 1, v128
	v_lshlrev_b32_e32 v129, 12, v171
	v_lshl_add_u32 v129, v188, 2, v129
	v_lshlrev_b32_e32 v132, 2, v188
	s_mov_b64 s[92:93], s[68:69]
	global_load_dwordx4 v[194:197], v128, s[92:93]
	global_load_dwordx4 v[198:201], v128, s[92:93] offset:64
	s_add_u32 s92, s92, 0x8000
	s_addc_u32 s93, s93, 0
	global_load_dwordx4 v[202:205], v128, s[92:93]
	global_load_dwordx4 v[206:209], v128, s[92:93] offset:64
	s_add_u32 s92, s92, 0x8000
	s_addc_u32 s93, s93, 0
	global_load_dwordx4 v[210:213], v128, s[92:93]
	global_load_dwordx4 v[214:217], v128, s[92:93] offset:64
	s_add_u32 s92, s92, 0x8000
	s_addc_u32 s93, s93, 0
	global_load_dwordx4 v[218:221], v128, s[92:93]
	global_load_dwordx4 v[222:225], v128, s[92:93] offset:64
	s_add_u32 s92, s92, 0x28000
	s_addc_u32 s93, s93, 0
	global_load_dwordx4 v[226:229], v128, s[92:93]
	global_load_dwordx4 v[230:233], v128, s[92:93] offset:64
	s_add_u32 s92, s92, 0x8000
	s_addc_u32 s93, s93, 0
	global_load_dwordx4 v[234:237], v128, s[92:93]
	global_load_dwordx4 v[238:241], v128, s[92:93] offset:64
	s_add_u32 s92, s92, 0x8000
	s_addc_u32 s93, s93, 0
	global_load_dwordx4 v[172:175], v128, s[92:93]
	global_load_dwordx4 v[176:179], v128, s[92:93] offset:64
	s_add_u32 s92, s92, 0x8000
	s_addc_u32 s93, s93, 0
	global_load_dwordx4 v[180:183], v128, s[92:93]
	global_load_dwordx4 v[184:187], v128, s[92:93] offset:64
	s_andn2_b32 s42, s16, 0x60
	v_and_b32_e32 v136, 3, v170
	v_lshl_or_b32 v136, v136, 5, s42
	v_lshlrev_b32_e32 v136, 2, v136
	s_add_u32 s88, s26, 0x3c10000
	s_addc_u32 s89, s27, 0
	global_load_dword v137, v136, s[88:89] sc1
	s_bfe_u32 s42, s17, 0x20006
	s_lshl_b32 s43, s10, 4
	s_lshl_b32 s42, s42, 2
	s_add_i32 s43, s43, s42
	v_lshl_add_u32 v130, v171, 6, s43
	v_and_b32_e32 v131, 48, v170
	v_lshl_add_u32 v131, v171, 6, v131
	v_xor_b32_e32 v134, 16, v170
	v_xor_b32_e32 v135, 32, v170
	v_lshlrev_b32_e32 v134, 2, v134
	v_lshlrev_b32_e32 v135, 2, v135
	v_cmp_gt_u32_e64 s[64:65], 16, v170
	s_mov_b32 s97, 0x5eed1234
	s_add_u32 s70, s26, 0x3800000
	s_addc_u32 s71, s27, 0
	s_add_u32 s72, s70, 0x400
	s_addc_u32 s73, s71, 0
	s_add_u32 s74, s72, 0x400
	s_addc_u32 s75, s73, 0
	s_add_u32 s76, s74, 0x400
	s_addc_u32 s77, s75, 0
	s_add_u32 s78, s76, 0x1400
	s_addc_u32 s79, s77, 0
	s_add_u32 s80, s78, 0x400
	s_addc_u32 s81, s79, 0
	s_add_u32 s82, s80, 0x400
	s_addc_u32 s83, s81, 0
	s_add_u32 s84, s82, 0x400
	s_addc_u32 s85, s83, 0
	s_waitcnt vmcnt(15)
	v_lshlrev_b32_e32 v138, 16, v194
	v_and_b32_e32 v139, s63, v194
	v_pk_add_f32 v[124:125], v[124:125], v[138:139]
	v_lshlrev_b32_e32 v190, 16, v195
	v_and_b32_e32 v191, s63, v195
	v_pk_add_f32 v[126:127], v[126:127], v[190:191]
	v_lshlrev_b32_e32 v138, 16, v196
	v_and_b32_e32 v139, s63, v196
	v_pk_add_f32 v[120:121], v[120:121], v[138:139]
	v_lshlrev_b32_e32 v190, 16, v197
	v_and_b32_e32 v191, s63, v197
	v_pk_add_f32 v[122:123], v[122:123], v[190:191]
	v_lshlrev_b32_e32 v138, 16, v198
	v_and_b32_e32 v139, s63, v198
	v_pk_add_f32 v[116:117], v[116:117], v[138:139]
	v_lshlrev_b32_e32 v190, 16, v199
	v_and_b32_e32 v191, s63, v199
	v_pk_add_f32 v[118:119], v[118:119], v[190:191]
	v_lshlrev_b32_e32 v138, 16, v200
	v_and_b32_e32 v139, s63, v200
	v_pk_add_f32 v[112:113], v[112:113], v[138:139]
	v_lshlrev_b32_e32 v190, 16, v201
	v_and_b32_e32 v191, s63, v201
	v_pk_add_f32 v[114:115], v[114:115], v[190:191]
	v_mul_f32_e32 v156, v120, v120
	v_mul_f32_e32 v189, v112, v112
	v_fmac_f32_e32 v156, v121, v121
	v_fmac_f32_e32 v189, v113, v113
	v_fmac_f32_e32 v156, v122, v122
	v_fmac_f32_e32 v189, v114, v114
	v_fmac_f32_e32 v156, v123, v123
	v_fmac_f32_e32 v189, v115, v115
	v_fmac_f32_e32 v156, v124, v124
	v_fmac_f32_e32 v189, v116, v116
	v_fmac_f32_e32 v156, v125, v125
	v_fmac_f32_e32 v189, v117, v117
	v_fmac_f32_e32 v156, v126, v126
	v_fmac_f32_e32 v189, v118, v118
	v_fmac_f32_e32 v156, v127, v127
	v_fmac_f32_e32 v189, v119, v119
	v_add_f32_e32 v156, v156, v189
	s_waitcnt vmcnt(13)
	v_lshlrev_b32_e32 v138, 16, v202
	v_and_b32_e32 v139, s63, v202
	v_pk_add_f32 v[108:109], v[108:109], v[138:139]
	v_lshlrev_b32_e32 v190, 16, v203
	v_and_b32_e32 v191, s63, v203
	v_pk_add_f32 v[110:111], v[110:111], v[190:191]
	v_lshlrev_b32_e32 v138, 16, v204
	v_and_b32_e32 v139, s63, v204
	v_pk_add_f32 v[104:105], v[104:105], v[138:139]
	v_lshlrev_b32_e32 v190, 16, v205
	v_and_b32_e32 v191, s63, v205
	v_pk_add_f32 v[106:107], v[106:107], v[190:191]
	v_lshlrev_b32_e32 v138, 16, v206
	v_and_b32_e32 v139, s63, v206
	v_pk_add_f32 v[100:101], v[100:101], v[138:139]
	v_lshlrev_b32_e32 v190, 16, v207
	v_and_b32_e32 v191, s63, v207
	v_pk_add_f32 v[102:103], v[102:103], v[190:191]
	v_lshlrev_b32_e32 v138, 16, v208
	v_and_b32_e32 v139, s63, v208
	v_pk_add_f32 v[96:97], v[96:97], v[138:139]
	v_lshlrev_b32_e32 v190, 16, v209
	v_and_b32_e32 v191, s63, v209
	v_pk_add_f32 v[98:99], v[98:99], v[190:191]
	v_mul_f32_e32 v157, v104, v104
	v_mul_f32_e32 v189, v96, v96
	v_fmac_f32_e32 v157, v105, v105
	v_fmac_f32_e32 v189, v97, v97
	v_fmac_f32_e32 v157, v106, v106
	v_fmac_f32_e32 v189, v98, v98
	v_fmac_f32_e32 v157, v107, v107
	v_fmac_f32_e32 v189, v99, v99
	v_fmac_f32_e32 v157, v108, v108
	v_fmac_f32_e32 v189, v100, v100
	v_fmac_f32_e32 v157, v109, v109
	v_fmac_f32_e32 v189, v101, v101
	v_fmac_f32_e32 v157, v110, v110
	v_fmac_f32_e32 v189, v102, v102
	v_fmac_f32_e32 v157, v111, v111
	v_fmac_f32_e32 v189, v103, v103
	v_add_f32_e32 v157, v157, v189
	s_waitcnt vmcnt(11)
	v_lshlrev_b32_e32 v138, 16, v210
	v_and_b32_e32 v139, s63, v210
	v_pk_add_f32 v[92:93], v[92:93], v[138:139]
	v_lshlrev_b32_e32 v190, 16, v211
	v_and_b32_e32 v191, s63, v211
	v_pk_add_f32 v[94:95], v[94:95], v[190:191]
	v_lshlrev_b32_e32 v138, 16, v212
	v_and_b32_e32 v139, s63, v212
	v_pk_add_f32 v[88:89], v[88:89], v[138:139]
	v_lshlrev_b32_e32 v190, 16, v213
	v_and_b32_e32 v191, s63, v213
	v_pk_add_f32 v[90:91], v[90:91], v[190:191]
	v_lshlrev_b32_e32 v138, 16, v214
	v_and_b32_e32 v139, s63, v214
	v_pk_add_f32 v[84:85], v[84:85], v[138:139]
	v_lshlrev_b32_e32 v190, 16, v215
	v_and_b32_e32 v191, s63, v215
	v_pk_add_f32 v[86:87], v[86:87], v[190:191]
	v_lshlrev_b32_e32 v138, 16, v216
	v_and_b32_e32 v139, s63, v216
	v_pk_add_f32 v[80:81], v[80:81], v[138:139]
	v_lshlrev_b32_e32 v190, 16, v217
	v_and_b32_e32 v191, s63, v217
	v_pk_add_f32 v[82:83], v[82:83], v[190:191]
	v_mul_f32_e32 v158, v88, v88
	v_mul_f32_e32 v189, v80, v80
	v_fmac_f32_e32 v158, v89, v89
	v_fmac_f32_e32 v189, v81, v81
	v_fmac_f32_e32 v158, v90, v90
	v_fmac_f32_e32 v189, v82, v82
	v_fmac_f32_e32 v158, v91, v91
	v_fmac_f32_e32 v189, v83, v83
	v_fmac_f32_e32 v158, v92, v92
	v_fmac_f32_e32 v189, v84, v84
	v_fmac_f32_e32 v158, v93, v93
	v_fmac_f32_e32 v189, v85, v85
	v_fmac_f32_e32 v158, v94, v94
	v_fmac_f32_e32 v189, v86, v86
	v_fmac_f32_e32 v158, v95, v95
	v_fmac_f32_e32 v189, v87, v87
	v_add_f32_e32 v158, v158, v189
	s_waitcnt vmcnt(9)
	v_lshlrev_b32_e32 v138, 16, v218
	v_and_b32_e32 v139, s63, v218
	v_pk_add_f32 v[76:77], v[76:77], v[138:139]
	v_lshlrev_b32_e32 v190, 16, v219
	v_and_b32_e32 v191, s63, v219
	v_pk_add_f32 v[78:79], v[78:79], v[190:191]
	v_lshlrev_b32_e32 v138, 16, v220
	v_and_b32_e32 v139, s63, v220
	v_pk_add_f32 v[72:73], v[72:73], v[138:139]
	v_lshlrev_b32_e32 v190, 16, v221
	v_and_b32_e32 v191, s63, v221
	v_pk_add_f32 v[74:75], v[74:75], v[190:191]
	v_lshlrev_b32_e32 v138, 16, v222
	v_and_b32_e32 v139, s63, v222
	v_pk_add_f32 v[68:69], v[68:69], v[138:139]
	v_lshlrev_b32_e32 v190, 16, v223
	v_and_b32_e32 v191, s63, v223
	v_pk_add_f32 v[70:71], v[70:71], v[190:191]
	v_lshlrev_b32_e32 v138, 16, v224
	v_and_b32_e32 v139, s63, v224
	v_pk_add_f32 v[64:65], v[64:65], v[138:139]
	v_lshlrev_b32_e32 v190, 16, v225
	v_and_b32_e32 v191, s63, v225
	v_pk_add_f32 v[66:67], v[66:67], v[190:191]
	v_mul_f32_e32 v159, v72, v72
	v_mul_f32_e32 v189, v64, v64
	v_fmac_f32_e32 v159, v73, v73
	v_fmac_f32_e32 v189, v65, v65
	v_fmac_f32_e32 v159, v74, v74
	v_fmac_f32_e32 v189, v66, v66
	v_fmac_f32_e32 v159, v75, v75
	v_fmac_f32_e32 v189, v67, v67
	v_fmac_f32_e32 v159, v76, v76
	v_fmac_f32_e32 v189, v68, v68
	v_fmac_f32_e32 v159, v77, v77
	v_fmac_f32_e32 v189, v69, v69
	v_fmac_f32_e32 v159, v78, v78
	v_fmac_f32_e32 v189, v70, v70
	v_fmac_f32_e32 v159, v79, v79
	v_fmac_f32_e32 v189, v71, v71
	v_add_f32_e32 v159, v159, v189
	s_waitcnt vmcnt(7)
	v_lshlrev_b32_e32 v138, 16, v226
	v_and_b32_e32 v139, s63, v226
	v_pk_add_f32 v[60:61], v[60:61], v[138:139]
	v_lshlrev_b32_e32 v190, 16, v227
	v_and_b32_e32 v191, s63, v227
	v_pk_add_f32 v[62:63], v[62:63], v[190:191]
	v_lshlrev_b32_e32 v138, 16, v228
	v_and_b32_e32 v139, s63, v228
	v_pk_add_f32 v[56:57], v[56:57], v[138:139]
	v_lshlrev_b32_e32 v190, 16, v229
	v_and_b32_e32 v191, s63, v229
	v_pk_add_f32 v[58:59], v[58:59], v[190:191]
	v_lshlrev_b32_e32 v138, 16, v230
	v_and_b32_e32 v139, s63, v230
	v_pk_add_f32 v[52:53], v[52:53], v[138:139]
	v_lshlrev_b32_e32 v190, 16, v231
	v_and_b32_e32 v191, s63, v231
	v_pk_add_f32 v[54:55], v[54:55], v[190:191]
	v_lshlrev_b32_e32 v138, 16, v232
	v_and_b32_e32 v139, s63, v232
	v_pk_add_f32 v[48:49], v[48:49], v[138:139]
	v_lshlrev_b32_e32 v190, 16, v233
	v_and_b32_e32 v191, s63, v233
	v_pk_add_f32 v[50:51], v[50:51], v[190:191]
	v_mul_f32_e32 v160, v56, v56
	v_mul_f32_e32 v189, v48, v48
	v_fmac_f32_e32 v160, v57, v57
	v_fmac_f32_e32 v189, v49, v49
	v_fmac_f32_e32 v160, v58, v58
	v_fmac_f32_e32 v189, v50, v50
	v_fmac_f32_e32 v160, v59, v59
	v_fmac_f32_e32 v189, v51, v51
	v_fmac_f32_e32 v160, v60, v60
	v_fmac_f32_e32 v189, v52, v52
	v_fmac_f32_e32 v160, v61, v61
	v_fmac_f32_e32 v189, v53, v53
	v_fmac_f32_e32 v160, v62, v62
	v_fmac_f32_e32 v189, v54, v54
	v_fmac_f32_e32 v160, v63, v63
	v_fmac_f32_e32 v189, v55, v55
	v_add_f32_e32 v160, v160, v189
	s_waitcnt vmcnt(5)
	v_lshlrev_b32_e32 v138, 16, v234
	v_and_b32_e32 v139, s63, v234
	v_pk_add_f32 v[44:45], v[44:45], v[138:139]
	v_lshlrev_b32_e32 v190, 16, v235
	v_and_b32_e32 v191, s63, v235
	v_pk_add_f32 v[46:47], v[46:47], v[190:191]
	v_lshlrev_b32_e32 v138, 16, v236
	v_and_b32_e32 v139, s63, v236
	v_pk_add_f32 v[40:41], v[40:41], v[138:139]
	v_lshlrev_b32_e32 v190, 16, v237
	v_and_b32_e32 v191, s63, v237
	v_pk_add_f32 v[42:43], v[42:43], v[190:191]
	v_lshlrev_b32_e32 v138, 16, v238
	v_and_b32_e32 v139, s63, v238
	v_pk_add_f32 v[36:37], v[36:37], v[138:139]
	v_lshlrev_b32_e32 v190, 16, v239
	v_and_b32_e32 v191, s63, v239
	v_pk_add_f32 v[38:39], v[38:39], v[190:191]
	v_lshlrev_b32_e32 v138, 16, v240
	v_and_b32_e32 v139, s63, v240
	v_pk_add_f32 v[32:33], v[32:33], v[138:139]
	v_lshlrev_b32_e32 v190, 16, v241
	v_and_b32_e32 v191, s63, v241
	v_pk_add_f32 v[34:35], v[34:35], v[190:191]
	v_mul_f32_e32 v161, v40, v40
	v_mul_f32_e32 v189, v32, v32
	v_fmac_f32_e32 v161, v41, v41
	v_fmac_f32_e32 v189, v33, v33
	v_fmac_f32_e32 v161, v42, v42
	v_fmac_f32_e32 v189, v34, v34
	v_fmac_f32_e32 v161, v43, v43
	v_fmac_f32_e32 v189, v35, v35
	v_fmac_f32_e32 v161, v44, v44
	v_fmac_f32_e32 v189, v36, v36
	v_fmac_f32_e32 v161, v45, v45
	v_fmac_f32_e32 v189, v37, v37
	v_fmac_f32_e32 v161, v46, v46
	v_fmac_f32_e32 v189, v38, v38
	v_fmac_f32_e32 v161, v47, v47
	v_fmac_f32_e32 v189, v39, v39
	v_add_f32_e32 v161, v161, v189
	s_waitcnt vmcnt(3)
	v_lshlrev_b32_e32 v138, 16, v172
	v_and_b32_e32 v139, s63, v172
	v_pk_add_f32 v[28:29], v[28:29], v[138:139]
	v_lshlrev_b32_e32 v190, 16, v173
	v_and_b32_e32 v191, s63, v173
	v_pk_add_f32 v[30:31], v[30:31], v[190:191]
	v_lshlrev_b32_e32 v138, 16, v174
	v_and_b32_e32 v139, s63, v174
	v_pk_add_f32 v[24:25], v[24:25], v[138:139]
	v_lshlrev_b32_e32 v190, 16, v175
	v_and_b32_e32 v191, s63, v175
	v_pk_add_f32 v[26:27], v[26:27], v[190:191]
	v_lshlrev_b32_e32 v138, 16, v176
	v_and_b32_e32 v139, s63, v176
	v_pk_add_f32 v[20:21], v[20:21], v[138:139]
	v_lshlrev_b32_e32 v190, 16, v177
	v_and_b32_e32 v191, s63, v177
	v_pk_add_f32 v[22:23], v[22:23], v[190:191]
	v_lshlrev_b32_e32 v138, 16, v178
	v_and_b32_e32 v139, s63, v178
	v_pk_add_f32 v[16:17], v[16:17], v[138:139]
	v_lshlrev_b32_e32 v190, 16, v179
	v_and_b32_e32 v191, s63, v179
	v_pk_add_f32 v[18:19], v[18:19], v[190:191]
	v_mul_f32_e32 v162, v24, v24
	v_mul_f32_e32 v189, v16, v16
	v_fmac_f32_e32 v162, v25, v25
	v_fmac_f32_e32 v189, v17, v17
	v_fmac_f32_e32 v162, v26, v26
	v_fmac_f32_e32 v189, v18, v18
	v_fmac_f32_e32 v162, v27, v27
	v_fmac_f32_e32 v189, v19, v19
	v_fmac_f32_e32 v162, v28, v28
	v_fmac_f32_e32 v189, v20, v20
	v_fmac_f32_e32 v162, v29, v29
	v_fmac_f32_e32 v189, v21, v21
	v_fmac_f32_e32 v162, v30, v30
	v_fmac_f32_e32 v189, v22, v22
	v_fmac_f32_e32 v162, v31, v31
	v_fmac_f32_e32 v189, v23, v23
	v_add_f32_e32 v162, v162, v189
	s_waitcnt vmcnt(1)
	v_lshlrev_b32_e32 v138, 16, v180
	v_and_b32_e32 v139, s63, v180
	v_pk_add_f32 v[12:13], v[12:13], v[138:139]
	v_lshlrev_b32_e32 v190, 16, v181
	v_and_b32_e32 v191, s63, v181
	v_pk_add_f32 v[14:15], v[14:15], v[190:191]
	v_lshlrev_b32_e32 v138, 16, v182
	v_and_b32_e32 v139, s63, v182
	v_pk_add_f32 v[8:9], v[8:9], v[138:139]
	v_lshlrev_b32_e32 v190, 16, v183
	v_and_b32_e32 v191, s63, v183
	v_pk_add_f32 v[10:11], v[10:11], v[190:191]
	v_lshlrev_b32_e32 v138, 16, v184
	v_and_b32_e32 v139, s63, v184
	v_pk_add_f32 v[4:5], v[4:5], v[138:139]
	v_lshlrev_b32_e32 v190, 16, v185
	v_and_b32_e32 v191, s63, v185
	v_pk_add_f32 v[6:7], v[6:7], v[190:191]
	v_lshlrev_b32_e32 v138, 16, v186
	v_and_b32_e32 v139, s63, v186
	v_pk_add_f32 v[0:1], v[0:1], v[138:139]
	v_lshlrev_b32_e32 v190, 16, v187
	v_and_b32_e32 v191, s63, v187
	v_pk_add_f32 v[2:3], v[2:3], v[190:191]
	v_mul_f32_e32 v163, v8, v8
	v_mul_f32_e32 v189, v0, v0
	v_fmac_f32_e32 v163, v9, v9
	v_fmac_f32_e32 v189, v1, v1
	v_fmac_f32_e32 v163, v10, v10
	v_fmac_f32_e32 v189, v2, v2
	v_fmac_f32_e32 v163, v11, v11
	v_fmac_f32_e32 v189, v3, v3
	v_fmac_f32_e32 v163, v12, v12
	v_fmac_f32_e32 v189, v4, v4
	v_fmac_f32_e32 v163, v13, v13
	v_fmac_f32_e32 v189, v5, v5
	v_fmac_f32_e32 v163, v14, v14
	v_fmac_f32_e32 v189, v6, v6
	v_fmac_f32_e32 v163, v15, v15
	v_fmac_f32_e32 v189, v7, v7
	v_add_f32_e32 v163, v163, v189
	ds_bpermute_b32 v172, v134, v156
	ds_bpermute_b32 v173, v134, v157
	ds_bpermute_b32 v138, v134, v158
	ds_bpermute_b32 v139, v134, v159
	ds_bpermute_b32 v188, v134, v160
	ds_bpermute_b32 v189, v134, v161
	ds_bpermute_b32 v190, v134, v162
	ds_bpermute_b32 v191, v134, v163
	s_waitcnt lgkmcnt(0)
	v_add_f32_e32 v156, v156, v172
	v_add_f32_e32 v157, v157, v173
	v_add_f32_e32 v158, v158, v138
	v_add_f32_e32 v159, v159, v139
	v_add_f32_e32 v160, v160, v188
	v_add_f32_e32 v161, v161, v189
	v_add_f32_e32 v162, v162, v190
	v_add_f32_e32 v163, v163, v191
	ds_bpermute_b32 v172, v135, v156
	ds_bpermute_b32 v173, v135, v157
	ds_bpermute_b32 v138, v135, v158
	ds_bpermute_b32 v139, v135, v159
	ds_bpermute_b32 v188, v135, v160
	ds_bpermute_b32 v189, v135, v161
	ds_bpermute_b32 v190, v135, v162
	ds_bpermute_b32 v191, v135, v163
	s_waitcnt lgkmcnt(0)
	v_add_f32_e32 v156, v156, v172
	v_add_f32_e32 v157, v157, v173
	v_add_f32_e32 v158, v158, v138
	v_add_f32_e32 v159, v159, v139
	v_add_f32_e32 v160, v160, v188
	v_add_f32_e32 v161, v161, v189
	v_add_f32_e32 v162, v162, v190
	v_add_f32_e32 v163, v163, v191
	v_max_f32_e32 v156, 0x00800000, v156
	v_max_f32_e32 v157, 0x00800000, v157
	v_max_f32_e32 v158, 0x00800000, v158
	v_max_f32_e32 v159, 0x00800000, v159
	v_max_f32_e32 v160, 0x00800000, v160
	v_max_f32_e32 v161, 0x00800000, v161
	v_max_f32_e32 v162, 0x00800000, v162
	v_max_f32_e32 v163, 0x00800000, v163
	s_waitcnt vmcnt(0)
	v_cmp_ne_u32_e32 vcc, s86, v137
	s_and_saveexec_b64 s[66:67], s[64:65]
	s_cbranch_vccnz .Lf11_st_far
	global_store_dword v130, v156, s[70:71]
	global_store_dword v130, v157, s[72:73]
	global_store_dword v130, v158, s[74:75]
	global_store_dword v130, v159, s[76:77]
	global_store_dword v130, v160, s[78:79]
	global_store_dword v130, v161, s[80:81]
	global_store_dword v130, v162, s[82:83]
	global_store_dword v130, v163, s[84:85]
	s_branch .Lf11_st_done
.Lf11_st_far:
	global_store_dword v130, v156, s[70:71] sc1
	global_store_dword v130, v157, s[72:73] sc1
	global_store_dword v130, v158, s[74:75] sc1
	global_store_dword v130, v159, s[76:77] sc1
	global_store_dword v130, v160, s[78:79] sc1
	global_store_dword v130, v161, s[80:81] sc1
	global_store_dword v130, v162, s[82:83] sc1
	global_store_dword v130, v163, s[84:85] sc1
.Lf11_st_done:
	s_or_b64 exec, exec, s[66:67]
	global_load_dwordx4 v[210:213], v132, s[22:23]
	global_load_dwordx4 v[214:217], v132, s[22:23] offset:16
	global_load_dwordx4 v[218:221], v132, s[22:23] offset:128
	global_load_dwordx4 v[222:225], v132, s[22:23] offset:144
	s_mov_b32 s87, 0
	s_nop 0
.Lf11_poll1:
	global_load_dwordx4 v[238:241], v131, s[84:85] sc1
	s_waitcnt vmcnt(0)
	v_min_u32_e32 v238, v238, v239
	v_min_u32_e32 v240, v240, v241
	v_min_u32_e32 v238, v238, v240
	v_cmp_eq_u32_e32 vcc, 0, v238
	s_cbranch_vccz .Lf11_poll
	s_sleep 8
	s_add_i32 s87, s87, 1
	s_cmp_lt_u32 s87, 0x4000
	s_cbranch_scc1 .Lf11_poll1
.Lf11_poll:
	global_load_dwordx4 v[172:175], v131, s[70:71] sc1
	global_load_dwordx4 v[176:179], v131, s[72:73] sc1
	global_load_dwordx4 v[180:183], v131, s[74:75] sc1
	global_load_dwordx4 v[184:187], v131, s[76:77] sc1
	global_load_dwordx4 v[226:229], v131, s[78:79] sc1
	global_load_dwordx4 v[230:233], v131, s[80:81] sc1
	global_load_dwordx4 v[234:237], v131, s[82:83] sc1
	global_load_dwordx4 v[238:241], v131, s[84:85] sc1
	s_waitcnt vmcnt(0)
	v_min_u32_e32 v194, v172, v173
	v_min3_u32 v194, v194, v174, v175
	v_min_u32_e32 v195, v176, v177
	v_min3_u32 v195, v195, v178, v179
	v_min_u32_e32 v196, v180, v181
	v_min3_u32 v196, v196, v182, v183
	v_min_u32_e32 v197, v184, v185
	v_min3_u32 v197, v197, v186, v187
	v_min_u32_e32 v198, v226, v227
	v_min3_u32 v198, v198, v228, v229
	v_min_u32_e32 v199, v230, v231
	v_min3_u32 v199, v199, v232, v233
	v_min_u32_e32 v200, v234, v235
	v_min3_u32 v200, v200, v236, v237
	v_min_u32_e32 v201, v238, v239
	v_min3_u32 v201, v201, v240, v241
	v_min_u32_e32 v194, v194, v195
	v_min_u32_e32 v196, v196, v197
	v_min_u32_e32 v198, v198, v199
	v_min_u32_e32 v200, v200, v201
	v_min_u32_e32 v194, v194, v196
	v_min_u32_e32 v198, v198, v200
	v_min_u32_e32 v194, v194, v198
	v_cmp_eq_u32_e32 vcc, 0, v194
	s_cbranch_vccz .Lf11_ready
	s_sleep 4
	s_add_i32 s87, s87, 1
	s_cmp_lt_u32 s87, 0x4000
	s_cbranch_scc1 .Lf11_poll
.Lf11_ready:
	s_mov_b64 s[94:95], s[24:25]
	s_mov_b32 s96, 0x3a800000
	v_mov_b32_e32 v133, 0x358637bd
	v_add_f32_e32 v172, v172, v173
	v_add_f32_e32 v174, v174, v175
	v_add_f32_e32 v172, v172, v174
	v_add_f32_e32 v176, v176, v177
	v_add_f32_e32 v178, v178, v179
	v_add_f32_e32 v176, v176, v178
	v_add_f32_e32 v180, v180, v181
	v_add_f32_e32 v182, v182, v183
	v_add_f32_e32 v180, v180, v182
	v_add_f32_e32 v184, v184, v185
	v_add_f32_e32 v186, v186, v187
	v_add_f32_e32 v184, v184, v186
	v_add_f32_e32 v226, v226, v227
	v_add_f32_e32 v228, v228, v229
	v_add_f32_e32 v226, v226, v228
	v_add_f32_e32 v230, v230, v231
	v_add_f32_e32 v232, v232, v233
	v_add_f32_e32 v230, v230, v232
	v_add_f32_e32 v234, v234, v235
	v_add_f32_e32 v236, v236, v237
	v_add_f32_e32 v234, v234, v236
	v_add_f32_e32 v238, v238, v239
	v_add_f32_e32 v240, v240, v241
	v_add_f32_e32 v238, v238, v240
	ds_bpermute_b32 v194, v134, v172
	ds_bpermute_b32 v195, v134, v176
	ds_bpermute_b32 v196, v134, v180
	ds_bpermute_b32 v197, v134, v184
	ds_bpermute_b32 v198, v134, v226
	ds_bpermute_b32 v199, v134, v230
	ds_bpermute_b32 v200, v134, v234
	ds_bpermute_b32 v201, v134, v238
	s_waitcnt lgkmcnt(0)
	v_add_f32_e32 v172, v172, v194
	v_add_f32_e32 v176, v176, v195
	v_add_f32_e32 v180, v180, v196
	v_add_f32_e32 v184, v184, v197
	v_add_f32_e32 v226, v226, v198
	v_add_f32_e32 v230, v230, v199
	v_add_f32_e32 v234, v234, v200
	v_add_f32_e32 v238, v238, v201
	ds_bpermute_b32 v194, v135, v172
	ds_bpermute_b32 v195, v135, v176
	ds_bpermute_b32 v196, v135, v180
	ds_bpermute_b32 v197, v135, v184
	ds_bpermute_b32 v198, v135, v226
	ds_bpermute_b32 v199, v135, v230
	ds_bpermute_b32 v200, v135, v234
	ds_bpermute_b32 v201, v135, v238
	s_waitcnt lgkmcnt(0)
	v_add_f32_e32 v172, v172, v194
	v_add_f32_e32 v176, v176, v195
	v_add_f32_e32 v180, v180, v196
	v_add_f32_e32 v184, v184, v197
	v_add_f32_e32 v226, v226, v198
	v_add_f32_e32 v230, v230, v199
	v_add_f32_e32 v234, v234, v200
	v_add_f32_e32 v238, v238, v201
	v_fma_f32 v172, v172, s96, v133
	v_fma_f32 v176, v176, s96, v133
	v_fma_f32 v180, v180, s96, v133
	v_fma_f32 v184, v184, s96, v133
	v_fma_f32 v226, v226, s96, v133
	v_fma_f32 v230, v230, s96, v133
	v_fma_f32 v234, v234, s96, v133
	v_fma_f32 v238, v238, s96, v133
	v_rsq_f32_e32 v174, v172
	v_rsq_f32_e32 v178, v176
	v_rsq_f32_e32 v182, v180
	v_rsq_f32_e32 v186, v184
	v_rsq_f32_e32 v228, v226
	v_rsq_f32_e32 v232, v230
	v_rsq_f32_e32 v236, v234
	v_rsq_f32_e32 v240, v238
	s_nop 0
	v_pk_mul_f32 v[124:125], v[124:125], v[174:175] op_sel_hi:[1,0]
	v_pk_mul_f32 v[126:127], v[126:127], v[174:175] op_sel_hi:[1,0]
	v_pk_mul_f32 v[120:121], v[120:121], v[174:175] op_sel_hi:[1,0]
	v_pk_mul_f32 v[122:123], v[122:123], v[174:175] op_sel_hi:[1,0]
	v_pk_mul_f32 v[116:117], v[116:117], v[174:175] op_sel_hi:[1,0]
	v_pk_mul_f32 v[118:119], v[118:119], v[174:175] op_sel_hi:[1,0]
	v_pk_mul_f32 v[112:113], v[112:113], v[174:175] op_sel_hi:[1,0]
	v_pk_mul_f32 v[114:115], v[114:115], v[174:175] op_sel_hi:[1,0]
	v_pk_mul_f32 v[124:125], v[124:125], v[210:211]
	v_pk_mul_f32 v[126:127], v[126:127], v[212:213]
	v_pk_mul_f32 v[120:121], v[120:121], v[214:215]
	v_pk_mul_f32 v[122:123], v[122:123], v[216:217]
	v_pk_mul_f32 v[116:117], v[116:117], v[218:219]
	v_pk_mul_f32 v[118:119], v[118:119], v[220:221]
	v_pk_mul_f32 v[112:113], v[112:113], v[222:223]
	v_pk_mul_f32 v[114:115], v[114:115], v[224:225]
	global_store_dwordx4 v129, v[124:127], s[94:95]
	global_store_dwordx4 v129, v[120:123], s[94:95] offset:16
	global_store_dwordx4 v129, v[116:119], s[94:95] offset:128
	global_store_dwordx4 v129, v[112:115], s[94:95] offset:144
	s_add_u32 s94, s94, 0x10000
	s_addc_u32 s95, s95, 0
	v_pk_mul_f32 v[108:109], v[108:109], v[178:179] op_sel_hi:[1,0]
	v_pk_mul_f32 v[110:111], v[110:111], v[178:179] op_sel_hi:[1,0]
	v_pk_mul_f32 v[104:105], v[104:105], v[178:179] op_sel_hi:[1,0]
	v_pk_mul_f32 v[106:107], v[106:107], v[178:179] op_sel_hi:[1,0]
	v_pk_mul_f32 v[100:101], v[100:101], v[178:179] op_sel_hi:[1,0]
	v_pk_mul_f32 v[102:103], v[102:103], v[178:179] op_sel_hi:[1,0]
	v_pk_mul_f32 v[96:97], v[96:97], v[178:179] op_sel_hi:[1,0]
	v_pk_mul_f32 v[98:99], v[98:99], v[178:179] op_sel_hi:[1,0]
	v_pk_mul_f32 v[108:109], v[108:109], v[210:211]
	v_pk_mul_f32 v[110:111], v[110:111], v[212:213]
	v_pk_mul_f32 v[104:105], v[104:105], v[214:215]
	v_pk_mul_f32 v[106:107], v[106:107], v[216:217]
	v_pk_mul_f32 v[100:101], v[100:101], v[218:219]
	v_pk_mul_f32 v[102:103], v[102:103], v[220:221]
	v_pk_mul_f32 v[96:97], v[96:97], v[222:223]
	v_pk_mul_f32 v[98:99], v[98:99], v[224:225]
	global_store_dwordx4 v129, v[108:111], s[94:95]
	global_store_dwordx4 v129, v[104:107], s[94:95] offset:16
	global_store_dwordx4 v129, v[100:103], s[94:95] offset:128
	global_store_dwordx4 v129, v[96:99], s[94:95] offset:144
	s_add_u32 s94, s94, 0x10000
	s_addc_u32 s95, s95, 0
	v_pk_mul_f32 v[92:93], v[92:93], v[182:183] op_sel_hi:[1,0]
	v_pk_mul_f32 v[94:95], v[94:95], v[182:183] op_sel_hi:[1,0]
	v_pk_mul_f32 v[88:89], v[88:89], v[182:183] op_sel_hi:[1,0]
	v_pk_mul_f32 v[90:91], v[90:91], v[182:183] op_sel_hi:[1,0]
	v_pk_mul_f32 v[84:85], v[84:85], v[182:183] op_sel_hi:[1,0]
	v_pk_mul_f32 v[86:87], v[86:87], v[182:183] op_sel_hi:[1,0]
	v_pk_mul_f32 v[80:81], v[80:81], v[182:183] op_sel_hi:[1,0]
	v_pk_mul_f32 v[82:83], v[82:83], v[182:183] op_sel_hi:[1,0]
	v_pk_mul_f32 v[92:93], v[92:93], v[210:211]
	v_pk_mul_f32 v[94:95], v[94:95], v[212:213]
	v_pk_mul_f32 v[88:89], v[88:89], v[214:215]
	v_pk_mul_f32 v[90:91], v[90:91], v[216:217]
	v_pk_mul_f32 v[84:85], v[84:85], v[218:219]
	v_pk_mul_f32 v[86:87], v[86:87], v[220:221]
	v_pk_mul_f32 v[80:81], v[80:81], v[222:223]
	v_pk_mul_f32 v[82:83], v[82:83], v[224:225]
	global_store_dwordx4 v129, v[92:95], s[94:95]
	global_store_dwordx4 v129, v[88:91], s[94:95] offset:16
	global_store_dwordx4 v129, v[84:87], s[94:95] offset:128
	global_store_dwordx4 v129, v[80:83], s[94:95] offset:144
	s_add_u32 s94, s94, 0x10000
	s_addc_u32 s95, s95, 0
	v_pk_mul_f32 v[76:77], v[76:77], v[186:187] op_sel_hi:[1,0]
	v_pk_mul_f32 v[78:79], v[78:79], v[186:187] op_sel_hi:[1,0]
	v_pk_mul_f32 v[72:73], v[72:73], v[186:187] op_sel_hi:[1,0]
	v_pk_mul_f32 v[74:75], v[74:75], v[186:187] op_sel_hi:[1,0]
	v_pk_mul_f32 v[68:69], v[68:69], v[186:187] op_sel_hi:[1,0]
	v_pk_mul_f32 v[70:71], v[70:71], v[186:187] op_sel_hi:[1,0]
	v_pk_mul_f32 v[64:65], v[64:65], v[186:187] op_sel_hi:[1,0]
	v_pk_mul_f32 v[66:67], v[66:67], v[186:187] op_sel_hi:[1,0]
	v_pk_mul_f32 v[76:77], v[76:77], v[210:211]
	v_pk_mul_f32 v[78:79], v[78:79], v[212:213]
	v_pk_mul_f32 v[72:73], v[72:73], v[214:215]
	v_pk_mul_f32 v[74:75], v[74:75], v[216:217]
	v_pk_mul_f32 v[68:69], v[68:69], v[218:219]
	v_pk_mul_f32 v[70:71], v[70:71], v[220:221]
	v_pk_mul_f32 v[64:65], v[64:65], v[222:223]
	v_pk_mul_f32 v[66:67], v[66:67], v[224:225]
	global_store_dwordx4 v129, v[76:79], s[94:95]
	global_store_dwordx4 v129, v[72:75], s[94:95] offset:16
	global_store_dwordx4 v129, v[68:71], s[94:95] offset:128
	global_store_dwordx4 v129, v[64:67], s[94:95] offset:144
	s_add_u32 s94, s94, 0x50000
	s_addc_u32 s95, s95, 0
	v_pk_mul_f32 v[60:61], v[60:61], v[228:229] op_sel_hi:[1,0]
	v_pk_mul_f32 v[62:63], v[62:63], v[228:229] op_sel_hi:[1,0]
	v_pk_mul_f32 v[56:57], v[56:57], v[228:229] op_sel_hi:[1,0]
	v_pk_mul_f32 v[58:59], v[58:59], v[228:229] op_sel_hi:[1,0]
	v_pk_mul_f32 v[52:53], v[52:53], v[228:229] op_sel_hi:[1,0]
	v_pk_mul_f32 v[54:55], v[54:55], v[228:229] op_sel_hi:[1,0]
	v_pk_mul_f32 v[48:49], v[48:49], v[228:229] op_sel_hi:[1,0]
	v_pk_mul_f32 v[50:51], v[50:51], v[228:229] op_sel_hi:[1,0]
	v_pk_mul_f32 v[60:61], v[60:61], v[210:211]
	v_pk_mul_f32 v[62:63], v[62:63], v[212:213]
	v_pk_mul_f32 v[56:57], v[56:57], v[214:215]
	v_pk_mul_f32 v[58:59], v[58:59], v[216:217]
	v_pk_mul_f32 v[52:53], v[52:53], v[218:219]
	v_pk_mul_f32 v[54:55], v[54:55], v[220:221]
	v_pk_mul_f32 v[48:49], v[48:49], v[222:223]
	v_pk_mul_f32 v[50:51], v[50:51], v[224:225]
	global_store_dwordx4 v129, v[60:63], s[94:95]
	global_store_dwordx4 v129, v[56:59], s[94:95] offset:16
	global_store_dwordx4 v129, v[52:55], s[94:95] offset:128
	global_store_dwordx4 v129, v[48:51], s[94:95] offset:144
	s_add_u32 s94, s94, 0x10000
	s_addc_u32 s95, s95, 0
	v_pk_mul_f32 v[44:45], v[44:45], v[232:233] op_sel_hi:[1,0]
	v_pk_mul_f32 v[46:47], v[46:47], v[232:233] op_sel_hi:[1,0]
	v_pk_mul_f32 v[40:41], v[40:41], v[232:233] op_sel_hi:[1,0]
	v_pk_mul_f32 v[42:43], v[42:43], v[232:233] op_sel_hi:[1,0]
	v_pk_mul_f32 v[36:37], v[36:37], v[232:233] op_sel_hi:[1,0]
	v_pk_mul_f32 v[38:39], v[38:39], v[232:233] op_sel_hi:[1,0]
	v_pk_mul_f32 v[32:33], v[32:33], v[232:233] op_sel_hi:[1,0]
	v_pk_mul_f32 v[34:35], v[34:35], v[232:233] op_sel_hi:[1,0]
	v_pk_mul_f32 v[44:45], v[44:45], v[210:211]
	v_pk_mul_f32 v[46:47], v[46:47], v[212:213]
	v_pk_mul_f32 v[40:41], v[40:41], v[214:215]
	v_pk_mul_f32 v[42:43], v[42:43], v[216:217]
	v_pk_mul_f32 v[36:37], v[36:37], v[218:219]
	v_pk_mul_f32 v[38:39], v[38:39], v[220:221]
	v_pk_mul_f32 v[32:33], v[32:33], v[222:223]
	v_pk_mul_f32 v[34:35], v[34:35], v[224:225]
	global_store_dwordx4 v129, v[44:47], s[94:95]
	global_store_dwordx4 v129, v[40:43], s[94:95] offset:16
	global_store_dwordx4 v129, v[36:39], s[94:95] offset:128
	global_store_dwordx4 v129, v[32:35], s[94:95] offset:144
	s_add_u32 s94, s94, 0x10000
	s_addc_u32 s95, s95, 0
	v_pk_mul_f32 v[28:29], v[28:29], v[236:237] op_sel_hi:[1,0]
	v_pk_mul_f32 v[30:31], v[30:31], v[236:237] op_sel_hi:[1,0]
	v_pk_mul_f32 v[24:25], v[24:25], v[236:237] op_sel_hi:[1,0]
	v_pk_mul_f32 v[26:27], v[26:27], v[236:237] op_sel_hi:[1,0]
	v_pk_mul_f32 v[20:21], v[20:21], v[236:237] op_sel_hi:[1,0]
	v_pk_mul_f32 v[22:23], v[22:23], v[236:237] op_sel_hi:[1,0]
	v_pk_mul_f32 v[16:17], v[16:17], v[236:237] op_sel_hi:[1,0]
	v_pk_mul_f32 v[18:19], v[18:19], v[236:237] op_sel_hi:[1,0]
	v_pk_mul_f32 v[28:29], v[28:29], v[210:211]
	v_pk_mul_f32 v[30:31], v[30:31], v[212:213]
	v_pk_mul_f32 v[24:25], v[24:25], v[214:215]
	v_pk_mul_f32 v[26:27], v[26:27], v[216:217]
	v_pk_mul_f32 v[20:21], v[20:21], v[218:219]
	v_pk_mul_f32 v[22:23], v[22:23], v[220:221]
	v_pk_mul_f32 v[16:17], v[16:17], v[222:223]
	v_pk_mul_f32 v[18:19], v[18:19], v[224:225]
	global_store_dwordx4 v129, v[28:31], s[94:95]
	global_store_dwordx4 v129, v[24:27], s[94:95] offset:16
	global_store_dwordx4 v129, v[20:23], s[94:95] offset:128
	global_store_dwordx4 v129, v[16:19], s[94:95] offset:144
	s_add_u32 s94, s94, 0x10000
	s_addc_u32 s95, s95, 0
	v_pk_mul_f32 v[12:13], v[12:13], v[240:241] op_sel_hi:[1,0]
	v_pk_mul_f32 v[14:15], v[14:15], v[240:241] op_sel_hi:[1,0]
	v_pk_mul_f32 v[8:9], v[8:9], v[240:241] op_sel_hi:[1,0]
	v_pk_mul_f32 v[10:11], v[10:11], v[240:241] op_sel_hi:[1,0]
	v_pk_mul_f32 v[4:5], v[4:5], v[240:241] op_sel_hi:[1,0]
	v_pk_mul_f32 v[6:7], v[6:7], v[240:241] op_sel_hi:[1,0]
	v_pk_mul_f32 v[0:1], v[0:1], v[240:241] op_sel_hi:[1,0]
	v_pk_mul_f32 v[2:3], v[2:3], v[240:241] op_sel_hi:[1,0]
	v_pk_mul_f32 v[12:13], v[12:13], v[210:211]
	v_pk_mul_f32 v[14:15], v[14:15], v[212:213]
	v_pk_mul_f32 v[8:9], v[8:9], v[214:215]
	v_pk_mul_f32 v[10:11], v[10:11], v[216:217]
	v_pk_mul_f32 v[4:5], v[4:5], v[218:219]
	v_pk_mul_f32 v[6:7], v[6:7], v[220:221]
	v_pk_mul_f32 v[0:1], v[0:1], v[222:223]
	v_pk_mul_f32 v[2:3], v[2:3], v[224:225]
	global_store_dwordx4 v129, v[12:15], s[94:95]
	global_store_dwordx4 v129, v[8:11], s[94:95] offset:16
	global_store_dwordx4 v129, v[4:7], s[94:95] offset:128
	global_store_dwordx4 v129, v[0:3], s[94:95] offset:144
	s_branch .Lf11_next
